# attn-static-prio-waves0-3
# speedup vs baseline: 1.0035x; 1.0035x over previous
.LBB0_469:
	s_abs_i32 s0, s3
	v_cvt_f32_u32_e32 v3, s0
	s_sub_i32 s5, 0, s0
	s_add_i32 s2, s3, 0x3ff
	s_movk_i32 s4, 0xff
	v_rcp_iflag_f32_e32 v3, v3
	s_ashr_i32 s6, s2, 31
	s_abs_i32 s2, s2
	s_ashr_i32 s1, s3, 31
	v_mul_f32_e32 v3, 0x4f7ffffe, v3
	v_cvt_u32_f32_e32 v3, v3
	v_cmp_lt_u32_e32 vcc, s4, v0
	v_readfirstlane_b32 s7, v3
	s_mul_i32 s5, s5, s7
	s_mul_hi_u32 s5, s7, s5
	s_add_i32 s7, s7, s5
	s_mul_hi_u32 s7, s2, s7
	s_cmpk_gt_u32 s70, 0xff
	s_cbranch_scc1 .Lattn_noprio
	s_setprio 1
.Lattn_noprio:
	s_mul_i32 s4, s7, s0
	s_sub_i32 s2, s2, s4
	s_xor_b32 s1, s6, s1
	s_add_i32 s4, s7, 1
	s_sub_i32 s5, s2, s0
	s_cmp_ge_u32 s2, s0
	s_cselect_b32 s4, s4, s7
	s_cselect_b32 s2, s5, s2
	s_add_i32 s5, s4, 1
	s_cmp_ge_u32 s2, s0
	s_cselect_b32 s0, s5, s4
	s_xor_b32 s0, s0, s1
	s_sub_i32 s0, s0, s1
	s_cmp_lt_i32 s0, 1
	v_lshlrev_b32_e32 v195, 4, v0
	v_and_b32_e32 v191, 3, v0
	s_cbranch_scc1 .LBB0_490
	s_cmp_lg_u32 0, -1
	s_cselect_b32 s2, 0, 0
	s_add_i32 s2, s2, 0x8000
	s_waitcnt lgkmcnt(0)
	s_add_u32 s33, s8, 0x5000000
	s_addc_u32 s34, s9, 0
	v_and_b32_e32 v253, 31, v0
	v_lshrrev_b32_e32 v3, 5, v252
	v_lshlrev_b32_e32 v5, 1, v0
	s_add_u32 s35, s8, 0x1000000
	v_lshlrev_b32_e32 v4, 3, v0
	v_and_b32_e32 v5, 32, v5
	v_and_b32_e32 v6, 0xc0, v195
	v_lshlrev_b32_e32 v7, 10, v3
	v_lshlrev_b32_e32 v8, 4, v253
	s_addc_u32 s46, s9, 0
	v_and_b32_e32 v20, 24, v4
	v_lshl_or_b32 v6, v3, 8, v6
	v_add3_u32 v228, 0, v7, v8
	v_add_u32_e32 v7, 0, v5
	s_add_u32 s47, s8, 0x7000000
	v_add3_u32 v229, v7, v20, v6
	v_lshlrev_b32_e32 v7, 9, v253
	s_addc_u32 s48, s9, 0
	v_lshl_or_b32 v22, v3, 3, v7
	v_lshlrev_b32_e32 v231, 4, v3
	v_lshlrev_b32_e32 v232, 9, v3
	v_lshrrev_b32_e32 v3, 3, v252
	s_add_u32 s49, s8, 0x7800000
	v_mov_b32_e32 v193, 0
	v_add_u32_e32 v5, s2, v5
	v_and_b32_e32 v194, 56, v4
	v_or_b32_e32 v4, 8, v3
	s_addc_u32 s50, s9, 0
	v_lshlrev_b32_e32 v192, 8, v252
	v_add3_u32 v230, v5, v20, v6
	v_lshlrev_b32_e32 v5, 6, v0
	v_lshlrev_b32_e32 v233, 7, v3
	v_lshlrev_b32_e32 v26, 10, v3
	v_lshlrev_b32_e32 v234, 7, v4
	v_lshlrev_b32_e32 v28, 10, v4
	v_or_b32_e32 v4, 16, v3
	v_or_b32_e32 v3, 24, v3
	s_add_u32 s51, s8, 0x8000000
	v_lshl_add_u64 v[34:35], s[8:9], 0, v[192:193]
	s_mov_b64 s[10:11], 0x7004000
	v_lshlrev_b32_e32 v192, 4, v191
	v_lshlrev_b32_e32 v18, 7, v252
	v_lshrrev_b32_e32 v254, 2, v252
	v_and_b32_e32 v24, 0xe00, v5
	v_lshlrev_b32_e32 v30, 10, v4
	v_lshlrev_b32_e32 v32, 10, v3
	v_xor_b32_e32 v2, 0x80000000, v2
	s_addc_u32 s52, s9, 0
	v_lshl_add_u64 v[196:197], v[34:35], 0, s[10:11]
	v_lshl_add_u64 v[34:35], s[8:9], 0, v[192:193]
	s_mov_b64 s[8:9], 0x7804000
	s_mul_i32 s1, s0, s73
	s_mov_b32 s7, 0
	v_cmp_gt_u32_e64 s[4:5], 32, v252
	v_lshlrev_b32_e32 v235, 7, v4
	v_lshlrev_b32_e32 v236, 7, v3
	v_mov_b32_e32 v3, v2
	v_mov_b32_e32 v4, v2
	v_mov_b32_e32 v5, v2
	v_mov_b32_e32 v6, v2
	v_mov_b32_e32 v7, v2
	v_mov_b32_e32 v8, v2
	v_mov_b32_e32 v9, v2
	v_mov_b32_e32 v10, v2
	v_mov_b32_e32 v11, v2
	v_mov_b32_e32 v12, v2
	v_mov_b32_e32 v13, v2
	v_mov_b32_e32 v14, v2
	v_mov_b32_e32 v15, v2
	v_mov_b32_e32 v16, v2
	v_mov_b32_e32 v17, v2
	v_lshl_add_u64 v[198:199], v[34:35], 0, s[8:9]
	v_lshlrev_b32_e32 v237, 7, v254
	s_mov_b64 s[36:37], 0
	v_lshlrev_b32_e32 v200, 1, v18
	v_lshlrev_b32_e32 v202, 1, v20
	s_mov_b64 s[8:9], 0x4000
	v_lshlrev_b32_e32 v238, 1, v22
	s_mov_b64 s[10:11], 0x8000
	s_mov_b64 s[12:13], 0xc000
	s_mov_b64 s[14:15], 0x10000
	s_mov_b64 s[16:17], 0x78000
	s_mov_b64 s[18:19], 0x70000
	s_mov_b64 s[22:23], 0x7c000
	s_mov_b64 s[24:25], 0x74000
	v_lshlrev_b32_e32 v204, 1, v24
	v_lshlrev_b32_e32 v206, 1, v26
	v_lshlrev_b32_e32 v208, 1, v28
	v_lshlrev_b32_e32 v210, 1, v30
	v_lshlrev_b32_e32 v212, 1, v32
	s_mov_b32 s53, 0
	s_branch .LBB0_475
